# K|V|Q and conv in-projection tiles too: first K iteration peeled with C=0 MFMAs, accumulator zeroing moves removed
# speedup vs baseline: 1.0066x; 1.0029x over previous
.LBB0_287:
	s_ashr_i32 s21, s20, 31
	s_lshl_b64 s[22:23], s[20:21], 19
	s_add_u32 s22, s80, s22
	s_addc_u32 s23, s81, s23
	s_and_b64 s[24:25], s[6:7], exec
	s_cselect_b32 s21, s23, s29
	s_cselect_b32 s36, s22, s28
	s_ashr_i32 s19, s18, 31
	s_lshl_b64 s[24:25], s[18:19], 19
	s_add_u32 s24, s40, s24
	s_addc_u32 s25, s41, s25
	s_and_b64 s[34:35], s[6:7], exec
	s_cselect_b32 s19, s25, s31
	s_cselect_b32 s37, s24, s30
	s_add_u32 s38, s30, 0x100
	s_addc_u32 s39, s31, 0
	s_add_u32 s28, s28, 0x40080
	s_addc_u32 s29, s29, 0
	s_mov_b32 s55, -2
	s_add_u32 s30, s28, 0xfffc0080
	s_addc_u32 s31, s29, -1
	s_add_i32 s56, 0, 0x10000
	s_cmp_eq_u32 s55, 12
	s_cselect_b32 s35, s21, s31
	s_cselect_b32 s34, s36, s30
	s_cselect_b32 s31, s19, s39
	s_cselect_b32 s30, s37, s38
	s_add_i32 s58, 0, 0x14000
	v_add_u32_e32 v166, s56, v147
	v_add_u32_e32 v182, s58, v147
	ds_read_b128 v[142:145], v166
	ds_read_b128 v[158:161], v166 offset:1024
	ds_read_b128 v[162:165], v166 offset:2048
	ds_read_b128 v[166:169], v166 offset:3072
	ds_read_b128 v[170:173], v182
	ds_read_b128 v[174:177], v182 offset:1024
	ds_read_b128 v[178:181], v182 offset:2048
	ds_read_b128 v[182:185], v182 offset:3072
	v_lshl_add_u64 v[224:225], s[28:29], 0, v[140:141]
	s_add_i32 m0, s44, 0xc000
	ds_read_b128 v[186:189], v157
	ds_read_b128 v[190:193], v157 offset:1024
	ds_read_b128 v[194:197], v157 offset:2048
	ds_read_b128 v[198:201], v157 offset:3072
	ds_read_b128 v[202:205], v157 offset:4096
	ds_read_b128 v[206:209], v157 offset:5120
	ds_read_b128 v[220:223], v157 offset:6144
	ds_read_b128 v[236:239], v157 offset:7168
	global_load_lds_dwordx4 v[224:225], off
	v_lshl_add_u64 v[224:225], s[28:29], 0, v[138:139]
	s_add_i32 m0, s44, 0xe000
	s_nop 0
	global_load_lds_dwordx4 v[224:225], off
	s_nop 0
	s_nop 0
	s_nop 0
	s_nop 0
	s_nop 0
	s_nop 0
	s_nop 0
	s_nop 0
	s_waitcnt vmcnt(8)
	s_waitcnt lgkmcnt(0)
	s_barrier
	s_waitcnt lgkmcnt(0)
	v_mfma_f32_16x16x32_bf16 v[126:129], v[142:145], v[186:189], 0
	v_mfma_f32_16x16x32_bf16 v[122:125], v[162:165], v[186:189], 0
	v_mfma_f32_16x16x32_bf16 v[110:113], v[142:145], v[194:197], 0
	v_mfma_f32_16x16x32_bf16 v[106:109], v[162:165], v[194:197], 0
	v_mfma_f32_16x16x32_bf16 v[94:97], v[142:145], v[202:205], 0
	v_mfma_f32_16x16x32_bf16 v[90:93], v[162:165], v[202:205], 0
	v_mfma_f32_16x16x32_bf16 v[78:81], v[142:145], v[220:223], 0
	v_mfma_f32_16x16x32_bf16 v[74:77], v[162:165], v[220:223], 0
	v_mfma_f32_16x16x32_bf16 v[126:129], v[158:161], v[190:193], v[126:129]
	v_mfma_f32_16x16x32_bf16 v[122:125], v[166:169], v[190:193], v[122:125]
	v_mfma_f32_16x16x32_bf16 v[110:113], v[158:161], v[198:201], v[110:113]
	v_mfma_f32_16x16x32_bf16 v[106:109], v[166:169], v[198:201], v[106:109]
	v_mfma_f32_16x16x32_bf16 v[94:97], v[158:161], v[206:209], v[94:97]
	v_mfma_f32_16x16x32_bf16 v[90:93], v[166:169], v[206:209], v[90:93]
	v_mfma_f32_16x16x32_bf16 v[78:81], v[158:161], v[236:239], v[78:81]
	v_mfma_f32_16x16x32_bf16 v[74:77], v[166:169], v[236:239], v[74:77]
	v_mfma_f32_16x16x32_bf16 v[118:121], v[170:173], v[186:189], 0
	v_mfma_f32_16x16x32_bf16 v[114:117], v[178:181], v[186:189], 0
	v_mfma_f32_16x16x32_bf16 v[102:105], v[170:173], v[194:197], 0
	v_mfma_f32_16x16x32_bf16 v[98:101], v[178:181], v[194:197], 0
	v_mfma_f32_16x16x32_bf16 v[86:89], v[170:173], v[202:205], 0
	v_mfma_f32_16x16x32_bf16 v[82:85], v[178:181], v[202:205], 0
	v_mfma_f32_16x16x32_bf16 v[70:73], v[170:173], v[220:223], 0
	v_mfma_f32_16x16x32_bf16 v[66:69], v[178:181], v[220:223], 0
	v_mfma_f32_16x16x32_bf16 v[118:121], v[174:177], v[190:193], v[118:121]
	v_mfma_f32_16x16x32_bf16 v[114:117], v[182:185], v[190:193], v[114:117]
	v_mfma_f32_16x16x32_bf16 v[102:105], v[174:177], v[198:201], v[102:105]
	v_mfma_f32_16x16x32_bf16 v[98:101], v[182:185], v[198:201], v[98:101]
	v_mfma_f32_16x16x32_bf16 v[86:89], v[174:177], v[206:209], v[86:89]
	v_mfma_f32_16x16x32_bf16 v[82:85], v[182:185], v[206:209], v[82:85]
	v_mfma_f32_16x16x32_bf16 v[70:73], v[174:177], v[236:239], v[70:73]
	v_mfma_f32_16x16x32_bf16 v[66:69], v[182:185], v[236:239], v[66:69]
	s_barrier
	s_add_i32 s56, s56, s27
	v_lshl_add_u64 v[224:225], s[30:31], 0, v[132:133]
	s_mov_b32 m0, s56
	ds_read_b128 v[186:189], v157 offset:16384
	ds_read_b128 v[190:193], v157 offset:17408
	ds_read_b128 v[194:197], v157 offset:18432
	ds_read_b128 v[198:201], v157 offset:19456
	ds_read_b128 v[202:205], v157 offset:20480
	ds_read_b128 v[206:209], v157 offset:21504
	ds_read_b128 v[220:223], v157 offset:22528
	ds_read_b128 v[236:239], v157 offset:23552
	global_load_lds_dwordx4 v[224:225], off
	s_add_i32 m0, s56, 0x2000
	s_add_u32 s56, s30, 0x40000
	v_lshl_add_u64 v[230:231], s[30:31], 0, v[136:137]
	s_addc_u32 s57, s31, 0
	s_add_i32 s58, s58, s27
	global_load_lds_dwordx4 v[230:231], off
	v_lshl_add_u64 v[240:241], s[56:57], 0, v[132:133]
	s_mov_b32 m0, s58
	v_lshl_add_u64 v[242:243], s[34:35], 0, v[134:135]
	global_load_lds_dwordx4 v[240:241], off
	v_lshl_add_u64 v[240:241], s[56:57], 0, v[136:137]
	s_add_i32 m0, s58, 0x2000
	s_nop 0
	global_load_lds_dwordx4 v[240:241], off
	v_lshl_add_u64 v[240:241], s[34:35], 0, v[130:131]
	s_mov_b32 m0, s44
	s_nop 0
	global_load_lds_dwordx4 v[240:241], off
	s_mov_b32 m0, s45
	s_nop 0
	global_load_lds_dwordx4 v[242:243], off
	s_nop 0
	s_nop 0
	s_nop 0
	s_waitcnt vmcnt(8)
	s_waitcnt lgkmcnt(0)
	s_barrier
	s_waitcnt lgkmcnt(0)
	v_mfma_f32_16x16x32_bf16 v[62:65], v[142:145], v[186:189], 0
	v_mfma_f32_16x16x32_bf16 v[58:61], v[162:165], v[186:189], 0
	v_mfma_f32_16x16x32_bf16 v[46:49], v[142:145], v[194:197], 0
	v_mfma_f32_16x16x32_bf16 v[42:45], v[162:165], v[194:197], 0
	v_mfma_f32_16x16x32_bf16 v[30:33], v[142:145], v[202:205], 0
	v_mfma_f32_16x16x32_bf16 v[26:29], v[162:165], v[202:205], 0
	v_mfma_f32_16x16x32_bf16 v[14:17], v[142:145], v[220:223], 0
	v_mfma_f32_16x16x32_bf16 v[10:13], v[162:165], v[220:223], 0
	v_mfma_f32_16x16x32_bf16 v[62:65], v[158:161], v[190:193], v[62:65]
	v_mfma_f32_16x16x32_bf16 v[58:61], v[166:169], v[190:193], v[58:61]
	v_mfma_f32_16x16x32_bf16 v[46:49], v[158:161], v[198:201], v[46:49]
	v_mfma_f32_16x16x32_bf16 v[42:45], v[166:169], v[198:201], v[42:45]
	v_mfma_f32_16x16x32_bf16 v[30:33], v[158:161], v[206:209], v[30:33]
	v_mfma_f32_16x16x32_bf16 v[26:29], v[166:169], v[206:209], v[26:29]
	v_mfma_f32_16x16x32_bf16 v[14:17], v[158:161], v[236:239], v[14:17]
	v_mfma_f32_16x16x32_bf16 v[10:13], v[166:169], v[236:239], v[10:13]
	v_mfma_f32_16x16x32_bf16 v[54:57], v[170:173], v[186:189], 0
	v_mfma_f32_16x16x32_bf16 v[50:53], v[178:181], v[186:189], 0
	v_mfma_f32_16x16x32_bf16 v[38:41], v[170:173], v[194:197], 0
	v_mfma_f32_16x16x32_bf16 v[34:37], v[178:181], v[194:197], 0
	v_mfma_f32_16x16x32_bf16 v[22:25], v[170:173], v[202:205], 0
	v_mfma_f32_16x16x32_bf16 v[18:21], v[178:181], v[202:205], 0
	v_mfma_f32_16x16x32_bf16 v[6:9], v[170:173], v[220:223], 0
	v_mfma_f32_16x16x32_bf16 v[2:5], v[178:181], v[220:223], 0
	v_mfma_f32_16x16x32_bf16 v[54:57], v[174:177], v[190:193], v[54:57]
	v_mfma_f32_16x16x32_bf16 v[50:53], v[182:185], v[190:193], v[50:53]
	v_mfma_f32_16x16x32_bf16 v[38:41], v[174:177], v[198:201], v[38:41]
	v_mfma_f32_16x16x32_bf16 v[34:37], v[182:185], v[198:201], v[34:37]
	v_mfma_f32_16x16x32_bf16 v[22:25], v[174:177], v[206:209], v[22:25]
	v_mfma_f32_16x16x32_bf16 v[18:21], v[182:185], v[206:209], v[18:21]
	v_mfma_f32_16x16x32_bf16 v[6:9], v[174:177], v[236:239], v[6:9]
	v_mfma_f32_16x16x32_bf16 v[2:5], v[182:185], v[236:239], v[2:5]
	s_barrier
	s_add_i32 s56, 0, 0x18000
	s_add_i32 s57, 0, 0x1c000
	v_add_u32_e32 v166, s56, v147
	v_add_u32_e32 v182, s57, v147
	ds_read_b128 v[142:145], v166
	ds_read_b128 v[158:161], v166 offset:1024
	ds_read_b128 v[162:165], v166 offset:2048
	ds_read_b128 v[166:169], v166 offset:3072
	ds_read_b128 v[170:173], v182
	ds_read_b128 v[174:177], v182 offset:1024
	ds_read_b128 v[178:181], v182 offset:2048
	ds_read_b128 v[182:185], v182 offset:3072
	s_add_u32 s34, s34, 0x40000
	s_addc_u32 s35, s35, 0
	s_mov_b32 m0, s43
	v_lshl_add_u64 v[244:245], s[34:35], 0, v[130:131]
	ds_read_b128 v[186:189], v157 offset:32768
	ds_read_b128 v[190:193], v157 offset:33792
	ds_read_b128 v[194:197], v157 offset:34816
	ds_read_b128 v[198:201], v157 offset:35840
	ds_read_b128 v[202:205], v157 offset:36864
	ds_read_b128 v[206:209], v157 offset:37888
	ds_read_b128 v[220:223], v157 offset:38912
	ds_read_b128 v[236:239], v157 offset:39936
	global_load_lds_dwordx4 v[244:245], off
	v_lshl_add_u64 v[244:245], s[34:35], 0, v[134:135]
	s_mov_b32 m0, s46
	s_nop 0
	global_load_lds_dwordx4 v[244:245], off
	s_nop 0
	s_nop 0
	s_nop 0
	s_nop 0
	s_nop 0
	s_nop 0
	s_nop 0
	s_waitcnt vmcnt(8)
	s_waitcnt lgkmcnt(0)
	s_barrier
	s_waitcnt lgkmcnt(0)
	v_mfma_f32_16x16x32_bf16 v[126:129], v[142:145], v[186:189], v[126:129]
	v_mfma_f32_16x16x32_bf16 v[122:125], v[162:165], v[186:189], v[122:125]
	v_mfma_f32_16x16x32_bf16 v[110:113], v[142:145], v[194:197], v[110:113]
	v_mfma_f32_16x16x32_bf16 v[106:109], v[162:165], v[194:197], v[106:109]
	v_mfma_f32_16x16x32_bf16 v[94:97], v[142:145], v[202:205], v[94:97]
	v_mfma_f32_16x16x32_bf16 v[90:93], v[162:165], v[202:205], v[90:93]
	v_mfma_f32_16x16x32_bf16 v[78:81], v[142:145], v[220:223], v[78:81]
	v_mfma_f32_16x16x32_bf16 v[74:77], v[162:165], v[220:223], v[74:77]
	v_mfma_f32_16x16x32_bf16 v[126:129], v[158:161], v[190:193], v[126:129]
	v_mfma_f32_16x16x32_bf16 v[122:125], v[166:169], v[190:193], v[122:125]
	v_mfma_f32_16x16x32_bf16 v[110:113], v[158:161], v[198:201], v[110:113]
	v_mfma_f32_16x16x32_bf16 v[106:109], v[166:169], v[198:201], v[106:109]
	v_mfma_f32_16x16x32_bf16 v[94:97], v[158:161], v[206:209], v[94:97]
	v_mfma_f32_16x16x32_bf16 v[90:93], v[166:169], v[206:209], v[90:93]
	v_mfma_f32_16x16x32_bf16 v[78:81], v[158:161], v[236:239], v[78:81]
	v_mfma_f32_16x16x32_bf16 v[74:77], v[166:169], v[236:239], v[74:77]
	v_mfma_f32_16x16x32_bf16 v[118:121], v[170:173], v[186:189], v[118:121]
	v_mfma_f32_16x16x32_bf16 v[114:117], v[178:181], v[186:189], v[114:117]
	v_mfma_f32_16x16x32_bf16 v[102:105], v[170:173], v[194:197], v[102:105]
	v_mfma_f32_16x16x32_bf16 v[98:101], v[178:181], v[194:197], v[98:101]
	v_mfma_f32_16x16x32_bf16 v[86:89], v[170:173], v[202:205], v[86:89]
	v_mfma_f32_16x16x32_bf16 v[82:85], v[178:181], v[202:205], v[82:85]
	v_mfma_f32_16x16x32_bf16 v[70:73], v[170:173], v[220:223], v[70:73]
	v_mfma_f32_16x16x32_bf16 v[66:69], v[178:181], v[220:223], v[66:69]
	v_mfma_f32_16x16x32_bf16 v[118:121], v[174:177], v[190:193], v[118:121]
	v_mfma_f32_16x16x32_bf16 v[114:117], v[182:185], v[190:193], v[114:117]
	v_mfma_f32_16x16x32_bf16 v[102:105], v[174:177], v[198:201], v[102:105]
	v_mfma_f32_16x16x32_bf16 v[98:101], v[182:185], v[198:201], v[98:101]
	v_mfma_f32_16x16x32_bf16 v[86:89], v[174:177], v[206:209], v[86:89]
	v_mfma_f32_16x16x32_bf16 v[82:85], v[182:185], v[206:209], v[82:85]
	v_mfma_f32_16x16x32_bf16 v[70:73], v[174:177], v[236:239], v[70:73]
	v_mfma_f32_16x16x32_bf16 v[66:69], v[182:185], v[236:239], v[66:69]
	s_barrier
	s_add_i32 s34, s56, s27
	v_lshl_add_u64 v[224:225], v[224:225], 0, s[96:97]
	s_mov_b32 m0, s34
	ds_read_b128 v[186:189], v157 offset:49152
	ds_read_b128 v[190:193], v157 offset:50176
	ds_read_b128 v[194:197], v157 offset:51200
	ds_read_b128 v[198:201], v157 offset:52224
	ds_read_b128 v[202:205], v157 offset:53248
	ds_read_b128 v[206:209], v157 offset:54272
	ds_read_b128 v[220:223], v157 offset:55296
	ds_read_b128 v[236:239], v157 offset:56320
	global_load_lds_dwordx4 v[224:225], off
	s_add_i32 m0, s34, 0x2000
	s_add_u32 s30, s30, 0x40080
	v_lshl_add_u64 v[224:225], v[230:231], 0, s[96:97]
	s_addc_u32 s31, s31, 0
	s_add_i32 s34, s57, s27
	global_load_lds_dwordx4 v[224:225], off
	v_lshl_add_u64 v[224:225], s[30:31], 0, v[132:133]
	s_mov_b32 m0, s34
	s_nop 0
	global_load_lds_dwordx4 v[224:225], off
	v_lshl_add_u64 v[224:225], s[30:31], 0, v[136:137]
	s_add_i32 m0, s34, 0x2000
	s_nop 0
	global_load_lds_dwordx4 v[224:225], off
	v_lshl_add_u64 v[224:225], v[240:241], 0, s[96:97]
	s_mov_b32 m0, s47
	s_nop 0
	global_load_lds_dwordx4 v[224:225], off
	v_lshl_add_u64 v[224:225], v[242:243], 0, s[96:97]
	s_mov_b32 m0, s48
	s_nop 0
	global_load_lds_dwordx4 v[224:225], off
	s_nop 0
	s_nop 0
	s_waitcnt vmcnt(8)
	s_waitcnt lgkmcnt(0)
	s_barrier
	s_waitcnt lgkmcnt(0)
	v_mfma_f32_16x16x32_bf16 v[62:65], v[142:145], v[186:189], v[62:65]
	v_mfma_f32_16x16x32_bf16 v[58:61], v[162:165], v[186:189], v[58:61]
	v_mfma_f32_16x16x32_bf16 v[46:49], v[142:145], v[194:197], v[46:49]
	v_mfma_f32_16x16x32_bf16 v[42:45], v[162:165], v[194:197], v[42:45]
	v_mfma_f32_16x16x32_bf16 v[30:33], v[142:145], v[202:205], v[30:33]
	v_mfma_f32_16x16x32_bf16 v[26:29], v[162:165], v[202:205], v[26:29]
	v_mfma_f32_16x16x32_bf16 v[14:17], v[142:145], v[220:223], v[14:17]
	v_mfma_f32_16x16x32_bf16 v[10:13], v[162:165], v[220:223], v[10:13]
	v_mfma_f32_16x16x32_bf16 v[62:65], v[158:161], v[190:193], v[62:65]
	v_mfma_f32_16x16x32_bf16 v[58:61], v[166:169], v[190:193], v[58:61]
	v_mfma_f32_16x16x32_bf16 v[46:49], v[158:161], v[198:201], v[46:49]
	v_mfma_f32_16x16x32_bf16 v[42:45], v[166:169], v[198:201], v[42:45]
	v_mfma_f32_16x16x32_bf16 v[30:33], v[158:161], v[206:209], v[30:33]
	v_mfma_f32_16x16x32_bf16 v[26:29], v[166:169], v[206:209], v[26:29]
	v_mfma_f32_16x16x32_bf16 v[14:17], v[158:161], v[236:239], v[14:17]
	v_mfma_f32_16x16x32_bf16 v[10:13], v[166:169], v[236:239], v[10:13]
	v_mfma_f32_16x16x32_bf16 v[54:57], v[170:173], v[186:189], v[54:57]
	v_mfma_f32_16x16x32_bf16 v[50:53], v[178:181], v[186:189], v[50:53]
	v_mfma_f32_16x16x32_bf16 v[38:41], v[170:173], v[194:197], v[38:41]
	v_mfma_f32_16x16x32_bf16 v[34:37], v[178:181], v[194:197], v[34:37]
	v_mfma_f32_16x16x32_bf16 v[22:25], v[170:173], v[202:205], v[22:25]
	v_mfma_f32_16x16x32_bf16 v[18:21], v[178:181], v[202:205], v[18:21]
	v_mfma_f32_16x16x32_bf16 v[6:9], v[170:173], v[220:223], v[6:9]
	v_mfma_f32_16x16x32_bf16 v[2:5], v[178:181], v[220:223], v[2:5]
	v_mfma_f32_16x16x32_bf16 v[54:57], v[174:177], v[190:193], v[54:57]
	v_mfma_f32_16x16x32_bf16 v[50:53], v[182:185], v[190:193], v[50:53]
	v_mfma_f32_16x16x32_bf16 v[38:41], v[174:177], v[198:201], v[38:41]
	v_mfma_f32_16x16x32_bf16 v[34:37], v[182:185], v[198:201], v[34:37]
	v_mfma_f32_16x16x32_bf16 v[22:25], v[174:177], v[206:209], v[22:25]
	v_mfma_f32_16x16x32_bf16 v[18:21], v[182:185], v[206:209], v[18:21]
	v_mfma_f32_16x16x32_bf16 v[6:9], v[174:177], v[236:239], v[6:9]
	v_mfma_f32_16x16x32_bf16 v[2:5], v[182:185], v[236:239], v[2:5]
	s_barrier
	s_add_i32 s55, s55, 2
	s_add_u32 s38, s38, 0x100
	s_addc_u32 s39, s39, 0
	s_add_u32 s28, s28, 0x100
	s_addc_u32 s29, s29, 0
	s_cmp_gt_u32 s55, 13

.LBB0_639:
	s_ashr_i32 s13, s12, 31
	s_lshl_b64 s[14:15], s[12:13], 19
	s_add_u32 s14, s80, s14
	s_addc_u32 s15, s81, s15
	s_and_b64 s[16:17], s[4:5], exec
	s_cselect_b32 s13, s15, s23
	s_cselect_b32 s19, s14, s22
	s_ashr_i32 s11, s10, 31
	s_lshl_b64 s[16:17], s[10:11], 19
	s_add_u32 s16, s26, s16
	s_addc_u32 s17, s27, s17
	s_and_b64 s[24:25], s[4:5], exec
	s_cselect_b32 s11, s17, s21
	s_cselect_b32 s41, s16, s20
	s_add_u32 s43, s20, 0x100
	s_addc_u32 s44, s21, 0
	s_add_u32 s20, s22, 0x40080
	s_addc_u32 s21, s23, 0
	s_mov_b32 s45, -2
	s_add_u32 s22, s20, 0xfffc0080
	s_addc_u32 s23, s21, -1
	s_add_i32 s46, 0, 0x10000
	s_cmp_eq_u32 s45, 12
	s_cselect_b32 s25, s13, s23
	s_cselect_b32 s24, s19, s22
	v_add_u32_e32 v150, s46, v159
	s_cselect_b32 s23, s11, s44
	s_cselect_b32 s22, s41, s43
	s_add_i32 s48, 0, 0x14000
	ds_read_b128 v[164:167], v150
	ds_read_b128 v[168:171], v150 offset:1024
	ds_read_b128 v[172:175], v150 offset:2048
	ds_read_b128 v[176:179], v150 offset:3072
	v_add_u32_e32 v150, s48, v159
	ds_read_b128 v[180:183], v150
	ds_read_b128 v[184:187], v150 offset:1024
	ds_read_b128 v[188:191], v150 offset:2048
	ds_read_b128 v[192:195], v150 offset:3072
	v_lshl_add_u64 v[150:151], s[20:21], 0, v[140:141]
	s_add_i32 m0, s30, 0xc000
	ds_read_b128 v[196:199], v162
	ds_read_b128 v[200:203], v162 offset:1024
	ds_read_b128 v[204:207], v162 offset:2048
	ds_read_b128 v[220:223], v162 offset:3072
	ds_read_b128 v[236:239], v162 offset:4096
	ds_read_b128 v[240:243], v162 offset:5120
	ds_read_b128 v[244:247], v162 offset:6144
	ds_read_b128 v[248:251], v162 offset:7168
	global_load_lds_dwordx4 v[150:151], off
	v_lshl_add_u64 v[150:151], s[20:21], 0, v[138:139]
	s_add_i32 m0, s30, 0xe000
	s_nop 0
	global_load_lds_dwordx4 v[150:151], off
	s_nop 0
	s_nop 0
	s_nop 0
	s_nop 0
	s_nop 0
	s_nop 0
	s_nop 0
	s_nop 0
	s_nop 0
	s_nop 0
	s_nop 0
	s_nop 0
	s_nop 0
	s_waitcnt vmcnt(8)
	s_waitcnt lgkmcnt(0)
	s_barrier
	s_waitcnt lgkmcnt(0)
	v_mfma_f32_16x16x32_bf16 v[126:129], v[164:167], v[196:199], 0
	v_mfma_f32_16x16x32_bf16 v[122:125], v[172:175], v[196:199], 0
	v_mfma_f32_16x16x32_bf16 v[118:121], v[164:167], v[204:207], 0
	v_mfma_f32_16x16x32_bf16 v[114:117], v[172:175], v[204:207], 0
	v_mfma_f32_16x16x32_bf16 v[110:113], v[164:167], v[236:239], 0
	v_mfma_f32_16x16x32_bf16 v[106:109], v[172:175], v[236:239], 0
	v_mfma_f32_16x16x32_bf16 v[102:105], v[164:167], v[244:247], 0
	v_mfma_f32_16x16x32_bf16 v[98:101], v[172:175], v[244:247], 0
	v_mfma_f32_16x16x32_bf16 v[126:129], v[168:171], v[200:203], v[126:129]
	v_mfma_f32_16x16x32_bf16 v[122:125], v[176:179], v[200:203], v[122:125]
	v_mfma_f32_16x16x32_bf16 v[118:121], v[168:171], v[220:223], v[118:121]
	v_mfma_f32_16x16x32_bf16 v[114:117], v[176:179], v[220:223], v[114:117]
	v_mfma_f32_16x16x32_bf16 v[110:113], v[168:171], v[240:243], v[110:113]
	v_mfma_f32_16x16x32_bf16 v[106:109], v[176:179], v[240:243], v[106:109]
	v_mfma_f32_16x16x32_bf16 v[102:105], v[168:171], v[248:251], v[102:105]
	v_mfma_f32_16x16x32_bf16 v[98:101], v[176:179], v[248:251], v[98:101]
	v_mfma_f32_16x16x32_bf16 v[94:97], v[180:183], v[196:199], 0
	v_mfma_f32_16x16x32_bf16 v[90:93], v[188:191], v[196:199], 0
	v_mfma_f32_16x16x32_bf16 v[86:89], v[180:183], v[204:207], 0
	v_mfma_f32_16x16x32_bf16 v[82:85], v[188:191], v[204:207], 0
	v_mfma_f32_16x16x32_bf16 v[78:81], v[180:183], v[236:239], 0
	v_mfma_f32_16x16x32_bf16 v[74:77], v[188:191], v[236:239], 0
	v_mfma_f32_16x16x32_bf16 v[70:73], v[180:183], v[244:247], 0
	v_mfma_f32_16x16x32_bf16 v[66:69], v[188:191], v[244:247], 0
	v_mfma_f32_16x16x32_bf16 v[94:97], v[184:187], v[200:203], v[94:97]
	v_mfma_f32_16x16x32_bf16 v[90:93], v[192:195], v[200:203], v[90:93]
	v_mfma_f32_16x16x32_bf16 v[86:89], v[184:187], v[220:223], v[86:89]
	v_mfma_f32_16x16x32_bf16 v[82:85], v[192:195], v[220:223], v[82:85]
	v_mfma_f32_16x16x32_bf16 v[78:81], v[184:187], v[240:243], v[78:81]
	v_mfma_f32_16x16x32_bf16 v[74:77], v[192:195], v[240:243], v[74:77]
	v_mfma_f32_16x16x32_bf16 v[70:73], v[184:187], v[248:251], v[70:73]
	v_mfma_f32_16x16x32_bf16 v[66:69], v[192:195], v[248:251], v[66:69]
	s_barrier
	s_add_i32 s46, s46, s28
	v_lshl_add_u64 v[150:151], s[22:23], 0, v[134:135]
	s_mov_b32 m0, s46
	ds_read_b128 v[196:199], v162 offset:16384
	ds_read_b128 v[200:203], v162 offset:17408
	ds_read_b128 v[204:207], v162 offset:18432
	ds_read_b128 v[220:223], v162 offset:19456
	ds_read_b128 v[236:239], v162 offset:20480
	ds_read_b128 v[240:243], v162 offset:21504
	ds_read_b128 v[244:247], v162 offset:22528
	ds_read_b128 v[248:251], v162 offset:23552
	global_load_lds_dwordx4 v[150:151], off
	s_add_i32 m0, s46, 0x2000
	s_add_u32 s46, s22, 0x40000
	v_lshl_add_u64 v[208:209], s[22:23], 0, v[130:131]
	s_addc_u32 s47, s23, 0
	s_add_i32 s48, s48, s28
	global_load_lds_dwordx4 v[208:209], off
	v_lshl_add_u64 v[224:225], s[46:47], 0, v[134:135]
	s_mov_b32 m0, s48
	v_lshl_add_u64 v[252:253], s[24:25], 0, v[132:133]
	global_load_lds_dwordx4 v[224:225], off
	v_lshl_add_u64 v[224:225], s[46:47], 0, v[130:131]
	s_add_i32 m0, s48, 0x2000
	s_nop 0
	global_load_lds_dwordx4 v[224:225], off
	v_lshl_add_u64 v[224:225], s[24:25], 0, v[136:137]
	s_mov_b32 m0, s30
	s_nop 0
	global_load_lds_dwordx4 v[224:225], off
	s_mov_b32 m0, s31
	s_nop 0
	global_load_lds_dwordx4 v[252:253], off
	s_nop 0
	s_nop 0
	s_nop 0
	s_waitcnt vmcnt(8)
	s_waitcnt lgkmcnt(0)
	s_barrier
	s_waitcnt lgkmcnt(0)
	v_mfma_f32_16x16x32_bf16 v[62:65], v[164:167], v[196:199], 0
	v_mfma_f32_16x16x32_bf16 v[58:61], v[172:175], v[196:199], 0
	v_mfma_f32_16x16x32_bf16 v[54:57], v[164:167], v[204:207], 0
	v_mfma_f32_16x16x32_bf16 v[50:53], v[172:175], v[204:207], 0
	v_mfma_f32_16x16x32_bf16 v[46:49], v[164:167], v[236:239], 0
	v_mfma_f32_16x16x32_bf16 v[42:45], v[172:175], v[236:239], 0
	v_mfma_f32_16x16x32_bf16 v[38:41], v[164:167], v[244:247], 0
	v_mfma_f32_16x16x32_bf16 v[34:37], v[172:175], v[244:247], 0
	v_mfma_f32_16x16x32_bf16 v[62:65], v[168:171], v[200:203], v[62:65]
	v_mfma_f32_16x16x32_bf16 v[58:61], v[176:179], v[200:203], v[58:61]
	v_mfma_f32_16x16x32_bf16 v[54:57], v[168:171], v[220:223], v[54:57]
	v_mfma_f32_16x16x32_bf16 v[50:53], v[176:179], v[220:223], v[50:53]
	v_mfma_f32_16x16x32_bf16 v[46:49], v[168:171], v[240:243], v[46:49]
	v_mfma_f32_16x16x32_bf16 v[42:45], v[176:179], v[240:243], v[42:45]
	v_mfma_f32_16x16x32_bf16 v[38:41], v[168:171], v[248:251], v[38:41]
	v_mfma_f32_16x16x32_bf16 v[34:37], v[176:179], v[248:251], v[34:37]
	v_mfma_f32_16x16x32_bf16 v[30:33], v[180:183], v[196:199], 0
	v_mfma_f32_16x16x32_bf16 v[26:29], v[188:191], v[196:199], 0
	v_mfma_f32_16x16x32_bf16 v[22:25], v[180:183], v[204:207], 0
	v_mfma_f32_16x16x32_bf16 v[18:21], v[188:191], v[204:207], 0
	v_mfma_f32_16x16x32_bf16 v[14:17], v[180:183], v[236:239], 0
	v_mfma_f32_16x16x32_bf16 v[10:13], v[188:191], v[236:239], 0
	v_mfma_f32_16x16x32_bf16 v[6:9], v[180:183], v[244:247], 0
	v_mfma_f32_16x16x32_bf16 v[2:5], v[188:191], v[244:247], 0
	v_mfma_f32_16x16x32_bf16 v[30:33], v[184:187], v[200:203], v[30:33]
	v_mfma_f32_16x16x32_bf16 v[26:29], v[192:195], v[200:203], v[26:29]
	v_mfma_f32_16x16x32_bf16 v[22:25], v[184:187], v[220:223], v[22:25]
	v_mfma_f32_16x16x32_bf16 v[18:21], v[192:195], v[220:223], v[18:21]
	v_mfma_f32_16x16x32_bf16 v[14:17], v[184:187], v[240:243], v[14:17]
	v_mfma_f32_16x16x32_bf16 v[10:13], v[192:195], v[240:243], v[10:13]
	v_mfma_f32_16x16x32_bf16 v[6:9], v[184:187], v[248:251], v[6:9]
	v_mfma_f32_16x16x32_bf16 v[2:5], v[192:195], v[248:251], v[2:5]
	s_barrier
	s_add_i32 s46, 0, 0x18000
	v_add_u32_e32 v163, s46, v159
	s_add_i32 s47, 0, 0x1c000
	ds_read_b128 v[164:167], v163
	ds_read_b128 v[168:171], v163 offset:1024
	ds_read_b128 v[172:175], v163 offset:2048
	ds_read_b128 v[176:179], v163 offset:3072
	v_add_u32_e32 v163, s47, v159
	ds_read_b128 v[180:183], v163
	ds_read_b128 v[184:187], v163 offset:1024
	ds_read_b128 v[188:191], v163 offset:2048
	ds_read_b128 v[192:195], v163 offset:3072
	s_add_u32 s24, s24, 0x40000
	s_addc_u32 s25, s25, 0
	s_mov_b32 m0, s34
	v_lshl_add_u64 v[230:231], s[24:25], 0, v[136:137]
	ds_read_b128 v[196:199], v162 offset:32768
	ds_read_b128 v[200:203], v162 offset:33792
	ds_read_b128 v[204:207], v162 offset:34816
	ds_read_b128 v[220:223], v162 offset:35840
	ds_read_b128 v[236:239], v162 offset:36864
	ds_read_b128 v[240:243], v162 offset:37888
	ds_read_b128 v[244:247], v162 offset:38912
	ds_read_b128 v[248:251], v162 offset:39936
	global_load_lds_dwordx4 v[230:231], off
	v_lshl_add_u64 v[230:231], s[24:25], 0, v[132:133]
	s_mov_b32 m0, s35
	s_nop 0
	global_load_lds_dwordx4 v[230:231], off
	s_nop 0
	s_nop 0
	s_nop 0
	s_nop 0
	s_nop 0
	s_nop 0
	s_nop 0
	s_waitcnt vmcnt(8)
	s_waitcnt lgkmcnt(0)
	s_barrier
	s_waitcnt lgkmcnt(0)
	v_mfma_f32_16x16x32_bf16 v[126:129], v[164:167], v[196:199], v[126:129]
	v_mfma_f32_16x16x32_bf16 v[122:125], v[172:175], v[196:199], v[122:125]
	v_mfma_f32_16x16x32_bf16 v[118:121], v[164:167], v[204:207], v[118:121]
	v_mfma_f32_16x16x32_bf16 v[114:117], v[172:175], v[204:207], v[114:117]
	v_mfma_f32_16x16x32_bf16 v[110:113], v[164:167], v[236:239], v[110:113]
	v_mfma_f32_16x16x32_bf16 v[106:109], v[172:175], v[236:239], v[106:109]
	v_mfma_f32_16x16x32_bf16 v[102:105], v[164:167], v[244:247], v[102:105]
	v_mfma_f32_16x16x32_bf16 v[98:101], v[172:175], v[244:247], v[98:101]
	v_mfma_f32_16x16x32_bf16 v[126:129], v[168:171], v[200:203], v[126:129]
	v_mfma_f32_16x16x32_bf16 v[122:125], v[176:179], v[200:203], v[122:125]
	v_mfma_f32_16x16x32_bf16 v[118:121], v[168:171], v[220:223], v[118:121]
	v_mfma_f32_16x16x32_bf16 v[114:117], v[176:179], v[220:223], v[114:117]
	v_mfma_f32_16x16x32_bf16 v[110:113], v[168:171], v[240:243], v[110:113]
	v_mfma_f32_16x16x32_bf16 v[106:109], v[176:179], v[240:243], v[106:109]
	v_mfma_f32_16x16x32_bf16 v[102:105], v[168:171], v[248:251], v[102:105]
	v_mfma_f32_16x16x32_bf16 v[98:101], v[176:179], v[248:251], v[98:101]
	v_mfma_f32_16x16x32_bf16 v[94:97], v[180:183], v[196:199], v[94:97]
	v_mfma_f32_16x16x32_bf16 v[90:93], v[188:191], v[196:199], v[90:93]
	v_mfma_f32_16x16x32_bf16 v[86:89], v[180:183], v[204:207], v[86:89]
	v_mfma_f32_16x16x32_bf16 v[82:85], v[188:191], v[204:207], v[82:85]
	v_mfma_f32_16x16x32_bf16 v[78:81], v[180:183], v[236:239], v[78:81]
	v_mfma_f32_16x16x32_bf16 v[74:77], v[188:191], v[236:239], v[74:77]
	v_mfma_f32_16x16x32_bf16 v[70:73], v[180:183], v[244:247], v[70:73]
	v_mfma_f32_16x16x32_bf16 v[66:69], v[188:191], v[244:247], v[66:69]
	v_mfma_f32_16x16x32_bf16 v[94:97], v[184:187], v[200:203], v[94:97]
	v_mfma_f32_16x16x32_bf16 v[90:93], v[192:195], v[200:203], v[90:93]
	v_mfma_f32_16x16x32_bf16 v[86:89], v[184:187], v[220:223], v[86:89]
	v_mfma_f32_16x16x32_bf16 v[82:85], v[192:195], v[220:223], v[82:85]
	v_mfma_f32_16x16x32_bf16 v[78:81], v[184:187], v[240:243], v[78:81]
	v_mfma_f32_16x16x32_bf16 v[74:77], v[192:195], v[240:243], v[74:77]
	v_mfma_f32_16x16x32_bf16 v[70:73], v[184:187], v[248:251], v[70:73]
	v_mfma_f32_16x16x32_bf16 v[66:69], v[192:195], v[248:251], v[66:69]
	s_barrier
	s_add_i32 s24, s46, s28
	v_lshl_add_u64 v[150:151], v[150:151], 0, s[96:97]
	s_mov_b32 m0, s24
	ds_read_b128 v[196:199], v162 offset:49152
	ds_read_b128 v[200:203], v162 offset:50176
	ds_read_b128 v[204:207], v162 offset:51200
	ds_read_b128 v[220:223], v162 offset:52224
	ds_read_b128 v[236:239], v162 offset:53248
	ds_read_b128 v[240:243], v162 offset:54272
	ds_read_b128 v[244:247], v162 offset:55296
	ds_read_b128 v[248:251], v162 offset:56320
	global_load_lds_dwordx4 v[150:151], off
	s_add_i32 m0, s24, 0x2000
	s_add_u32 s22, s22, 0x40080
	v_lshl_add_u64 v[150:151], v[208:209], 0, s[96:97]
	s_addc_u32 s23, s23, 0
	s_add_i32 s24, s47, s28
	global_load_lds_dwordx4 v[150:151], off
	v_lshl_add_u64 v[150:151], s[22:23], 0, v[134:135]
	s_mov_b32 m0, s24
	s_nop 0
	global_load_lds_dwordx4 v[150:151], off
	v_lshl_add_u64 v[150:151], s[22:23], 0, v[130:131]
	s_add_i32 m0, s24, 0x2000
	s_nop 0
	global_load_lds_dwordx4 v[150:151], off
	v_lshl_add_u64 v[150:151], v[224:225], 0, s[96:97]
	s_mov_b32 m0, s36
	s_nop 0
	global_load_lds_dwordx4 v[150:151], off
	v_lshl_add_u64 v[150:151], v[252:253], 0, s[96:97]
	s_mov_b32 m0, s37
	s_nop 0
	global_load_lds_dwordx4 v[150:151], off
	s_nop 0
	s_nop 0
	s_waitcnt vmcnt(8)
	s_waitcnt lgkmcnt(0)
	s_barrier
	s_waitcnt lgkmcnt(0)
	v_mfma_f32_16x16x32_bf16 v[62:65], v[164:167], v[196:199], v[62:65]
	v_mfma_f32_16x16x32_bf16 v[58:61], v[172:175], v[196:199], v[58:61]
	v_mfma_f32_16x16x32_bf16 v[54:57], v[164:167], v[204:207], v[54:57]
	v_mfma_f32_16x16x32_bf16 v[50:53], v[172:175], v[204:207], v[50:53]
	v_mfma_f32_16x16x32_bf16 v[46:49], v[164:167], v[236:239], v[46:49]
	v_mfma_f32_16x16x32_bf16 v[42:45], v[172:175], v[236:239], v[42:45]
	v_mfma_f32_16x16x32_bf16 v[38:41], v[164:167], v[244:247], v[38:41]
	v_mfma_f32_16x16x32_bf16 v[34:37], v[172:175], v[244:247], v[34:37]
	v_mfma_f32_16x16x32_bf16 v[62:65], v[168:171], v[200:203], v[62:65]
	v_mfma_f32_16x16x32_bf16 v[58:61], v[176:179], v[200:203], v[58:61]
	v_mfma_f32_16x16x32_bf16 v[54:57], v[168:171], v[220:223], v[54:57]
	v_mfma_f32_16x16x32_bf16 v[50:53], v[176:179], v[220:223], v[50:53]
	v_mfma_f32_16x16x32_bf16 v[46:49], v[168:171], v[240:243], v[46:49]
	v_mfma_f32_16x16x32_bf16 v[42:45], v[176:179], v[240:243], v[42:45]
	v_mfma_f32_16x16x32_bf16 v[38:41], v[168:171], v[248:251], v[38:41]
	v_mfma_f32_16x16x32_bf16 v[34:37], v[176:179], v[248:251], v[34:37]
	v_mfma_f32_16x16x32_bf16 v[30:33], v[180:183], v[196:199], v[30:33]
	v_mfma_f32_16x16x32_bf16 v[26:29], v[188:191], v[196:199], v[26:29]
	v_mfma_f32_16x16x32_bf16 v[22:25], v[180:183], v[204:207], v[22:25]
	v_mfma_f32_16x16x32_bf16 v[18:21], v[188:191], v[204:207], v[18:21]
	v_mfma_f32_16x16x32_bf16 v[14:17], v[180:183], v[236:239], v[14:17]
	v_mfma_f32_16x16x32_bf16 v[10:13], v[188:191], v[236:239], v[10:13]
	v_mfma_f32_16x16x32_bf16 v[6:9], v[180:183], v[244:247], v[6:9]
	v_mfma_f32_16x16x32_bf16 v[2:5], v[188:191], v[244:247], v[2:5]
	v_mfma_f32_16x16x32_bf16 v[30:33], v[184:187], v[200:203], v[30:33]
	v_mfma_f32_16x16x32_bf16 v[26:29], v[192:195], v[200:203], v[26:29]
	v_mfma_f32_16x16x32_bf16 v[22:25], v[184:187], v[220:223], v[22:25]
	v_mfma_f32_16x16x32_bf16 v[18:21], v[192:195], v[220:223], v[18:21]
	v_mfma_f32_16x16x32_bf16 v[14:17], v[184:187], v[240:243], v[14:17]
	v_mfma_f32_16x16x32_bf16 v[10:13], v[192:195], v[240:243], v[10:13]
	v_mfma_f32_16x16x32_bf16 v[6:9], v[184:187], v[248:251], v[6:9]
	v_mfma_f32_16x16x32_bf16 v[2:5], v[192:195], v[248:251], v[2:5]
	s_barrier
	s_add_i32 s45, s45, 2
	s_add_u32 s43, s43, 0x100
	s_addc_u32 s44, s44, 0
	s_add_u32 s20, s20, 0x100
	s_addc_u32 s21, s21, 0
	s_cmp_gt_u32 s45, 13
.LBB0_640:
	s_add_u32 s22, s20, 0xfffc0080
	s_addc_u32 s23, s21, -1
	s_add_i32 s46, 0, 0x10000
	s_cmp_eq_u32 s45, 12
	s_cselect_b32 s25, s13, s23
	s_cselect_b32 s24, s19, s22
	v_add_u32_e32 v150, s46, v159
	s_cselect_b32 s23, s11, s44
	s_cselect_b32 s22, s41, s43
	s_add_i32 s48, 0, 0x14000
	ds_read_b128 v[164:167], v150
	ds_read_b128 v[168:171], v150 offset:1024
	ds_read_b128 v[172:175], v150 offset:2048
	ds_read_b128 v[176:179], v150 offset:3072
	v_add_u32_e32 v150, s48, v159
	ds_read_b128 v[180:183], v150
	ds_read_b128 v[184:187], v150 offset:1024
	ds_read_b128 v[188:191], v150 offset:2048
	ds_read_b128 v[192:195], v150 offset:3072
	v_lshl_add_u64 v[150:151], s[20:21], 0, v[140:141]
	s_add_i32 m0, s30, 0xc000
	ds_read_b128 v[196:199], v162
	ds_read_b128 v[200:203], v162 offset:1024
	ds_read_b128 v[204:207], v162 offset:2048
	ds_read_b128 v[220:223], v162 offset:3072
	ds_read_b128 v[236:239], v162 offset:4096
	ds_read_b128 v[240:243], v162 offset:5120
	ds_read_b128 v[244:247], v162 offset:6144
	ds_read_b128 v[248:251], v162 offset:7168
	global_load_lds_dwordx4 v[150:151], off
	v_lshl_add_u64 v[150:151], s[20:21], 0, v[138:139]
	s_add_i32 m0, s30, 0xe000
	s_nop 0
	global_load_lds_dwordx4 v[150:151], off
	s_nop 0
	s_nop 0
	s_nop 0
	s_nop 0
	s_nop 0
	s_nop 0
	s_nop 0
	s_nop 0
	s_nop 0
	s_nop 0
	s_nop 0
	s_nop 0
	s_nop 0
	s_nop 0
	s_nop 0
	s_nop 0
	s_nop 0
	s_nop 0
	s_nop 0
	s_nop 0
	s_nop 0
	s_nop 0
	s_nop 0
	s_nop 0
	s_waitcnt vmcnt(8)
	s_waitcnt lgkmcnt(0)
	s_barrier
	s_waitcnt lgkmcnt(0)
	v_mfma_f32_16x16x32_bf16 v[126:129], v[164:167], v[196:199], v[126:129]
	v_mfma_f32_16x16x32_bf16 v[122:125], v[172:175], v[196:199], v[122:125]
	v_mfma_f32_16x16x32_bf16 v[118:121], v[164:167], v[204:207], v[118:121]
	v_mfma_f32_16x16x32_bf16 v[114:117], v[172:175], v[204:207], v[114:117]
	v_mfma_f32_16x16x32_bf16 v[110:113], v[164:167], v[236:239], v[110:113]
	v_mfma_f32_16x16x32_bf16 v[106:109], v[172:175], v[236:239], v[106:109]
	v_mfma_f32_16x16x32_bf16 v[102:105], v[164:167], v[244:247], v[102:105]
	v_mfma_f32_16x16x32_bf16 v[98:101], v[172:175], v[244:247], v[98:101]
	v_mfma_f32_16x16x32_bf16 v[126:129], v[168:171], v[200:203], v[126:129]
	v_mfma_f32_16x16x32_bf16 v[122:125], v[176:179], v[200:203], v[122:125]
	v_mfma_f32_16x16x32_bf16 v[118:121], v[168:171], v[220:223], v[118:121]
	v_mfma_f32_16x16x32_bf16 v[114:117], v[176:179], v[220:223], v[114:117]
	v_mfma_f32_16x16x32_bf16 v[110:113], v[168:171], v[240:243], v[110:113]
	v_mfma_f32_16x16x32_bf16 v[106:109], v[176:179], v[240:243], v[106:109]
	v_mfma_f32_16x16x32_bf16 v[102:105], v[168:171], v[248:251], v[102:105]
	v_mfma_f32_16x16x32_bf16 v[98:101], v[176:179], v[248:251], v[98:101]
	v_mfma_f32_16x16x32_bf16 v[94:97], v[180:183], v[196:199], v[94:97]
	v_mfma_f32_16x16x32_bf16 v[90:93], v[188:191], v[196:199], v[90:93]
	v_mfma_f32_16x16x32_bf16 v[86:89], v[180:183], v[204:207], v[86:89]
	v_mfma_f32_16x16x32_bf16 v[82:85], v[188:191], v[204:207], v[82:85]
	v_mfma_f32_16x16x32_bf16 v[78:81], v[180:183], v[236:239], v[78:81]
	v_mfma_f32_16x16x32_bf16 v[74:77], v[188:191], v[236:239], v[74:77]
	v_mfma_f32_16x16x32_bf16 v[70:73], v[180:183], v[244:247], v[70:73]
	v_mfma_f32_16x16x32_bf16 v[66:69], v[188:191], v[244:247], v[66:69]
	v_mfma_f32_16x16x32_bf16 v[94:97], v[184:187], v[200:203], v[94:97]
	v_mfma_f32_16x16x32_bf16 v[90:93], v[192:195], v[200:203], v[90:93]
	v_mfma_f32_16x16x32_bf16 v[86:89], v[184:187], v[220:223], v[86:89]
	v_mfma_f32_16x16x32_bf16 v[82:85], v[192:195], v[220:223], v[82:85]
	v_mfma_f32_16x16x32_bf16 v[78:81], v[184:187], v[240:243], v[78:81]
	v_mfma_f32_16x16x32_bf16 v[74:77], v[192:195], v[240:243], v[74:77]
	v_mfma_f32_16x16x32_bf16 v[70:73], v[184:187], v[248:251], v[70:73]
	v_mfma_f32_16x16x32_bf16 v[66:69], v[192:195], v[248:251], v[66:69]
	s_barrier
	s_add_i32 s46, s46, s28
	v_lshl_add_u64 v[150:151], s[22:23], 0, v[134:135]
	s_mov_b32 m0, s46
	ds_read_b128 v[196:199], v162 offset:16384
	ds_read_b128 v[200:203], v162 offset:17408
	ds_read_b128 v[204:207], v162 offset:18432
	ds_read_b128 v[220:223], v162 offset:19456
	ds_read_b128 v[236:239], v162 offset:20480
	ds_read_b128 v[240:243], v162 offset:21504
	ds_read_b128 v[244:247], v162 offset:22528
	ds_read_b128 v[248:251], v162 offset:23552
	global_load_lds_dwordx4 v[150:151], off
	s_add_i32 m0, s46, 0x2000
	s_add_u32 s46, s22, 0x40000
	v_lshl_add_u64 v[208:209], s[22:23], 0, v[130:131]
	s_addc_u32 s47, s23, 0
	s_add_i32 s48, s48, s28
	global_load_lds_dwordx4 v[208:209], off
	v_lshl_add_u64 v[224:225], s[46:47], 0, v[134:135]
	s_mov_b32 m0, s48
	v_lshl_add_u64 v[252:253], s[24:25], 0, v[132:133]
	global_load_lds_dwordx4 v[224:225], off
	v_lshl_add_u64 v[224:225], s[46:47], 0, v[130:131]
	s_add_i32 m0, s48, 0x2000
	s_nop 0
	global_load_lds_dwordx4 v[224:225], off
	v_lshl_add_u64 v[224:225], s[24:25], 0, v[136:137]
	s_mov_b32 m0, s30
	s_nop 0
	global_load_lds_dwordx4 v[224:225], off
	s_mov_b32 m0, s31
	s_nop 0
	global_load_lds_dwordx4 v[252:253], off
	s_nop 0
	s_nop 0
	s_nop 0
	s_waitcnt vmcnt(8)
	s_waitcnt lgkmcnt(0)
	s_barrier
	s_waitcnt lgkmcnt(0)
	v_mfma_f32_16x16x32_bf16 v[62:65], v[164:167], v[196:199], v[62:65]
	v_mfma_f32_16x16x32_bf16 v[58:61], v[172:175], v[196:199], v[58:61]
	v_mfma_f32_16x16x32_bf16 v[54:57], v[164:167], v[204:207], v[54:57]
	v_mfma_f32_16x16x32_bf16 v[50:53], v[172:175], v[204:207], v[50:53]
	v_mfma_f32_16x16x32_bf16 v[46:49], v[164:167], v[236:239], v[46:49]
	v_mfma_f32_16x16x32_bf16 v[42:45], v[172:175], v[236:239], v[42:45]
	v_mfma_f32_16x16x32_bf16 v[38:41], v[164:167], v[244:247], v[38:41]
	v_mfma_f32_16x16x32_bf16 v[34:37], v[172:175], v[244:247], v[34:37]
	v_mfma_f32_16x16x32_bf16 v[62:65], v[168:171], v[200:203], v[62:65]
	v_mfma_f32_16x16x32_bf16 v[58:61], v[176:179], v[200:203], v[58:61]
	v_mfma_f32_16x16x32_bf16 v[54:57], v[168:171], v[220:223], v[54:57]
	v_mfma_f32_16x16x32_bf16 v[50:53], v[176:179], v[220:223], v[50:53]
	v_mfma_f32_16x16x32_bf16 v[46:49], v[168:171], v[240:243], v[46:49]
	v_mfma_f32_16x16x32_bf16 v[42:45], v[176:179], v[240:243], v[42:45]
	v_mfma_f32_16x16x32_bf16 v[38:41], v[168:171], v[248:251], v[38:41]
	v_mfma_f32_16x16x32_bf16 v[34:37], v[176:179], v[248:251], v[34:37]
	v_mfma_f32_16x16x32_bf16 v[30:33], v[180:183], v[196:199], v[30:33]
	v_mfma_f32_16x16x32_bf16 v[26:29], v[188:191], v[196:199], v[26:29]
	v_mfma_f32_16x16x32_bf16 v[22:25], v[180:183], v[204:207], v[22:25]
	v_mfma_f32_16x16x32_bf16 v[18:21], v[188:191], v[204:207], v[18:21]
	v_mfma_f32_16x16x32_bf16 v[14:17], v[180:183], v[236:239], v[14:17]
	v_mfma_f32_16x16x32_bf16 v[10:13], v[188:191], v[236:239], v[10:13]
	v_mfma_f32_16x16x32_bf16 v[6:9], v[180:183], v[244:247], v[6:9]
	v_mfma_f32_16x16x32_bf16 v[2:5], v[188:191], v[244:247], v[2:5]
	v_mfma_f32_16x16x32_bf16 v[30:33], v[184:187], v[200:203], v[30:33]
	v_mfma_f32_16x16x32_bf16 v[26:29], v[192:195], v[200:203], v[26:29]
	v_mfma_f32_16x16x32_bf16 v[22:25], v[184:187], v[220:223], v[22:25]
	v_mfma_f32_16x16x32_bf16 v[18:21], v[192:195], v[220:223], v[18:21]
	v_mfma_f32_16x16x32_bf16 v[14:17], v[184:187], v[240:243], v[14:17]
	v_mfma_f32_16x16x32_bf16 v[10:13], v[192:195], v[240:243], v[10:13]
	v_mfma_f32_16x16x32_bf16 v[6:9], v[184:187], v[248:251], v[6:9]
	v_mfma_f32_16x16x32_bf16 v[2:5], v[192:195], v[248:251], v[2:5]
	s_barrier
	s_add_i32 s46, 0, 0x18000
	v_add_u32_e32 v163, s46, v159
	s_add_i32 s47, 0, 0x1c000
	ds_read_b128 v[164:167], v163
	ds_read_b128 v[168:171], v163 offset:1024
	ds_read_b128 v[172:175], v163 offset:2048
	ds_read_b128 v[176:179], v163 offset:3072
	v_add_u32_e32 v163, s47, v159
	ds_read_b128 v[180:183], v163
	ds_read_b128 v[184:187], v163 offset:1024
	ds_read_b128 v[188:191], v163 offset:2048
	ds_read_b128 v[192:195], v163 offset:3072
	s_add_u32 s24, s24, 0x40000
	s_addc_u32 s25, s25, 0
	s_mov_b32 m0, s34
	v_lshl_add_u64 v[230:231], s[24:25], 0, v[136:137]
	ds_read_b128 v[196:199], v162 offset:32768
	ds_read_b128 v[200:203], v162 offset:33792
	ds_read_b128 v[204:207], v162 offset:34816
	ds_read_b128 v[220:223], v162 offset:35840
	ds_read_b128 v[236:239], v162 offset:36864
	ds_read_b128 v[240:243], v162 offset:37888
	ds_read_b128 v[244:247], v162 offset:38912
	ds_read_b128 v[248:251], v162 offset:39936
	global_load_lds_dwordx4 v[230:231], off
	v_lshl_add_u64 v[230:231], s[24:25], 0, v[132:133]
	s_mov_b32 m0, s35
	s_nop 0
	global_load_lds_dwordx4 v[230:231], off
	s_nop 0
	s_nop 0
	s_nop 0
	s_nop 0
	s_nop 0
	s_nop 0
	s_nop 0
	s_waitcnt vmcnt(8)
	s_waitcnt lgkmcnt(0)
	s_barrier
	s_waitcnt lgkmcnt(0)
	v_mfma_f32_16x16x32_bf16 v[126:129], v[164:167], v[196:199], v[126:129]
	v_mfma_f32_16x16x32_bf16 v[122:125], v[172:175], v[196:199], v[122:125]
	v_mfma_f32_16x16x32_bf16 v[118:121], v[164:167], v[204:207], v[118:121]
	v_mfma_f32_16x16x32_bf16 v[114:117], v[172:175], v[204:207], v[114:117]
	v_mfma_f32_16x16x32_bf16 v[110:113], v[164:167], v[236:239], v[110:113]
	v_mfma_f32_16x16x32_bf16 v[106:109], v[172:175], v[236:239], v[106:109]
	v_mfma_f32_16x16x32_bf16 v[102:105], v[164:167], v[244:247], v[102:105]
	v_mfma_f32_16x16x32_bf16 v[98:101], v[172:175], v[244:247], v[98:101]
	v_mfma_f32_16x16x32_bf16 v[126:129], v[168:171], v[200:203], v[126:129]
	v_mfma_f32_16x16x32_bf16 v[122:125], v[176:179], v[200:203], v[122:125]
	v_mfma_f32_16x16x32_bf16 v[118:121], v[168:171], v[220:223], v[118:121]
	v_mfma_f32_16x16x32_bf16 v[114:117], v[176:179], v[220:223], v[114:117]
	v_mfma_f32_16x16x32_bf16 v[110:113], v[168:171], v[240:243], v[110:113]
	v_mfma_f32_16x16x32_bf16 v[106:109], v[176:179], v[240:243], v[106:109]
	v_mfma_f32_16x16x32_bf16 v[102:105], v[168:171], v[248:251], v[102:105]
	v_mfma_f32_16x16x32_bf16 v[98:101], v[176:179], v[248:251], v[98:101]
	v_mfma_f32_16x16x32_bf16 v[94:97], v[180:183], v[196:199], v[94:97]
	v_mfma_f32_16x16x32_bf16 v[90:93], v[188:191], v[196:199], v[90:93]
	v_mfma_f32_16x16x32_bf16 v[86:89], v[180:183], v[204:207], v[86:89]
	v_mfma_f32_16x16x32_bf16 v[82:85], v[188:191], v[204:207], v[82:85]
	v_mfma_f32_16x16x32_bf16 v[78:81], v[180:183], v[236:239], v[78:81]
	v_mfma_f32_16x16x32_bf16 v[74:77], v[188:191], v[236:239], v[74:77]
	v_mfma_f32_16x16x32_bf16 v[70:73], v[180:183], v[244:247], v[70:73]
	v_mfma_f32_16x16x32_bf16 v[66:69], v[188:191], v[244:247], v[66:69]
	v_mfma_f32_16x16x32_bf16 v[94:97], v[184:187], v[200:203], v[94:97]
	v_mfma_f32_16x16x32_bf16 v[90:93], v[192:195], v[200:203], v[90:93]
	v_mfma_f32_16x16x32_bf16 v[86:89], v[184:187], v[220:223], v[86:89]
	v_mfma_f32_16x16x32_bf16 v[82:85], v[192:195], v[220:223], v[82:85]
	v_mfma_f32_16x16x32_bf16 v[78:81], v[184:187], v[240:243], v[78:81]
	v_mfma_f32_16x16x32_bf16 v[74:77], v[192:195], v[240:243], v[74:77]
	v_mfma_f32_16x16x32_bf16 v[70:73], v[184:187], v[248:251], v[70:73]
	v_mfma_f32_16x16x32_bf16 v[66:69], v[192:195], v[248:251], v[66:69]
	s_barrier
	s_add_i32 s24, s46, s28
	v_lshl_add_u64 v[150:151], v[150:151], 0, s[96:97]
	s_mov_b32 m0, s24
	ds_read_b128 v[196:199], v162 offset:49152
	ds_read_b128 v[200:203], v162 offset:50176
	ds_read_b128 v[204:207], v162 offset:51200
	ds_read_b128 v[220:223], v162 offset:52224
	ds_read_b128 v[236:239], v162 offset:53248
	ds_read_b128 v[240:243], v162 offset:54272
	ds_read_b128 v[244:247], v162 offset:55296
	ds_read_b128 v[248:251], v162 offset:56320
	global_load_lds_dwordx4 v[150:151], off
	s_add_i32 m0, s24, 0x2000
	s_add_u32 s22, s22, 0x40080
	v_lshl_add_u64 v[150:151], v[208:209], 0, s[96:97]
	s_addc_u32 s23, s23, 0
	s_add_i32 s24, s47, s28
	global_load_lds_dwordx4 v[150:151], off
	v_lshl_add_u64 v[150:151], s[22:23], 0, v[134:135]
	s_mov_b32 m0, s24
	s_nop 0
	global_load_lds_dwordx4 v[150:151], off
	v_lshl_add_u64 v[150:151], s[22:23], 0, v[130:131]
	s_add_i32 m0, s24, 0x2000
	s_nop 0
	global_load_lds_dwordx4 v[150:151], off
	v_lshl_add_u64 v[150:151], v[224:225], 0, s[96:97]
	s_mov_b32 m0, s36
	s_nop 0
	global_load_lds_dwordx4 v[150:151], off
	v_lshl_add_u64 v[150:151], v[252:253], 0, s[96:97]
	s_mov_b32 m0, s37
	s_nop 0
	global_load_lds_dwordx4 v[150:151], off
	s_nop 0
	s_nop 0
	s_waitcnt vmcnt(8)
	s_waitcnt lgkmcnt(0)
	s_barrier
	s_waitcnt lgkmcnt(0)
	v_mfma_f32_16x16x32_bf16 v[62:65], v[164:167], v[196:199], v[62:65]
	v_mfma_f32_16x16x32_bf16 v[58:61], v[172:175], v[196:199], v[58:61]
	v_mfma_f32_16x16x32_bf16 v[54:57], v[164:167], v[204:207], v[54:57]
	v_mfma_f32_16x16x32_bf16 v[50:53], v[172:175], v[204:207], v[50:53]
	v_mfma_f32_16x16x32_bf16 v[46:49], v[164:167], v[236:239], v[46:49]
	v_mfma_f32_16x16x32_bf16 v[42:45], v[172:175], v[236:239], v[42:45]
	v_mfma_f32_16x16x32_bf16 v[38:41], v[164:167], v[244:247], v[38:41]
	v_mfma_f32_16x16x32_bf16 v[34:37], v[172:175], v[244:247], v[34:37]
	v_mfma_f32_16x16x32_bf16 v[62:65], v[168:171], v[200:203], v[62:65]
	v_mfma_f32_16x16x32_bf16 v[58:61], v[176:179], v[200:203], v[58:61]
	v_mfma_f32_16x16x32_bf16 v[54:57], v[168:171], v[220:223], v[54:57]
	v_mfma_f32_16x16x32_bf16 v[50:53], v[176:179], v[220:223], v[50:53]
	v_mfma_f32_16x16x32_bf16 v[46:49], v[168:171], v[240:243], v[46:49]
	v_mfma_f32_16x16x32_bf16 v[42:45], v[176:179], v[240:243], v[42:45]
	v_mfma_f32_16x16x32_bf16 v[38:41], v[168:171], v[248:251], v[38:41]
	v_mfma_f32_16x16x32_bf16 v[34:37], v[176:179], v[248:251], v[34:37]
	v_mfma_f32_16x16x32_bf16 v[30:33], v[180:183], v[196:199], v[30:33]
	v_mfma_f32_16x16x32_bf16 v[26:29], v[188:191], v[196:199], v[26:29]
	v_mfma_f32_16x16x32_bf16 v[22:25], v[180:183], v[204:207], v[22:25]
	v_mfma_f32_16x16x32_bf16 v[18:21], v[188:191], v[204:207], v[18:21]
	v_mfma_f32_16x16x32_bf16 v[14:17], v[180:183], v[236:239], v[14:17]
	v_mfma_f32_16x16x32_bf16 v[10:13], v[188:191], v[236:239], v[10:13]
	v_mfma_f32_16x16x32_bf16 v[6:9], v[180:183], v[244:247], v[6:9]
	v_mfma_f32_16x16x32_bf16 v[2:5], v[188:191], v[244:247], v[2:5]
	v_mfma_f32_16x16x32_bf16 v[30:33], v[184:187], v[200:203], v[30:33]
	v_mfma_f32_16x16x32_bf16 v[26:29], v[192:195], v[200:203], v[26:29]
	v_mfma_f32_16x16x32_bf16 v[22:25], v[184:187], v[220:223], v[22:25]
	v_mfma_f32_16x16x32_bf16 v[18:21], v[192:195], v[220:223], v[18:21]
	v_mfma_f32_16x16x32_bf16 v[14:17], v[184:187], v[240:243], v[14:17]
	v_mfma_f32_16x16x32_bf16 v[10:13], v[192:195], v[240:243], v[10:13]
	v_mfma_f32_16x16x32_bf16 v[6:9], v[184:187], v[248:251], v[6:9]
	v_mfma_f32_16x16x32_bf16 v[2:5], v[192:195], v[248:251], v[2:5]
	s_barrier
	s_add_i32 s45, s45, 2
	s_add_u32 s43, s43, 0x100
	s_addc_u32 s44, s44, 0
	s_add_u32 s20, s20, 0x100
	s_addc_u32 s21, s21, 0
	s_cmp_gt_u32 s45, 13
	s_cbranch_scc0 .LBB0_640
	s_and_b64 vcc, exec, s[8:9]
	s_cbranch_vccz .LBB0_643
	s_barrier
